# MLP-up GEMM epilogue de-serialised: bias and row-statistic loads of a tile issued once at the top of the epilogue instead of per 8-column group, per-group waits removed
# speedup vs baseline: 1.4686x; 1.0054x over previous
;     __device__ __forceinline__ void operator()(const f32x4 (&acc)[2][2][4][2], const pg8::Unit& u, int wr, int wc, int fr, int fq) const {
;     ...
;                 const size_t row = (size_t)(row0 + ai * 128 + m * 16);
;                 float ssq = 0.f, rstd = 1.f;
;                 if constexpr (MODE == 8) rstd = 1.f / sqrtf(rs[row] * (1.f / DM) + EPS);
; #pragma unroll
;                 for (int bj = 0; bj < 2; ++bj) {
;                     const int col = col0 + bj * 128;
;                     f32x4 v0 = acc[ai][bj][m][0], v1 = acc[ai][bj][m][1];
;                     if constexpr (MODE == 0 || MODE == 1) { v0 = v0 * scale; v1 = v1 * scale; }
;                     if constexpr (MODE == 6) { float* p = of + row * IDXW + col; *(f32x4*)p = v0; *(f32x4*)(p + 4) = v1; }
;                     else if constexpr (MODE == 0) {
;                         if (u.pn >= COL_BV / 256) {
;                             const float x8[8] = {v0[0], v0[1], v0[2], v0[3], v1[0], v1[1], v1[2], v1[3]};
;                             *(u32x2*)((unsigned char*)aux + row * 1024 + (col - COL_BV)) = to_fp8x8(x8);
;                         } else { u32x4 w; w.x = pk2(v0[0], v0[1]); w.y = pk2(v0[2], v0[3]); w.z = pk2(v1[0], v1[1]); w.w = pk2(v1[2], v1[3]);
;                             *(u32x4*)(ob + row * QKVW + col) = w; }
;                     } else if constexpr (MODE == 1) {
;                         const f32x4 b0 = *(const f32x4*)(vec + col), b1 = *(const f32x4*)(vec + col + 4);
;                         float r[8];
; #pragma unroll
;                         for (int i = 0; i < 4; ++i) { r[i] = 1.f / (1.f + __expf(-(v0[i] + b0[i]))); r[4 + i] = 1.f / (1.f + __expf(-(v1[i] + b1[i]))); }
;                         u32x4 w; w.x = pk2(r[0], r[1]); w.y = pk2(r[2], r[3]); w.z = pk2(r[4], r[5]); w.w = pk2(r[6], r[7]);
;                         *(u32x4*)(ob + row * 4096 + col) = w;
;                     } else if constexpr (MODE == 2 || MODE == 3) {
;                         const u32x4 g = *(const u32x4*)(aux + row * 4096 + (MODE == 3 ? 2048 : 0) + col);
;                         float r[8] = {v0[0], v0[1], v0[2], v0[3], v1[0], v1[1], v1[2], v1[3]};
;                         const unsigned gw[4] = {g.x, g.y, g.z, g.w};
; #pragma unroll
;                         for (int i = 0; i < 4; ++i) { r[2 * i] *= bf2f(gw[i] & 0xffffu); r[2 * i + 1] *= __builtin_bit_cast(float, gw[i] & 0xffff0000u); }
.LBB0_35:
	v_lshl_add_u32 v144, s9, 8, v148
	v_lshl_or_b32 v146, s8, 8, v150
	v_readlane_b32 s8, v251, 21
	v_ashrrev_i32_e32 v145, 31, v144
	v_readlane_b32 s9, v251, 22
	s_mov_b32 s10, 0xf800000
	s_nop 0
	v_lshl_add_u64 v[138:139], v[144:145], 2, s[8:9]
	global_load_dword v214, v[138:139], off
	v_or_b32_e32 v224, 16, v144
	v_ashrrev_i32_e32 v225, 31, v224
	v_lshl_add_u64 v[224:225], v[224:225], 2, s[8:9]
	global_load_dword v215, v[224:225], off
	v_or_b32_e32 v224, 32, v144
	v_ashrrev_i32_e32 v225, 31, v224
	v_lshl_add_u64 v[224:225], v[224:225], 2, s[8:9]
	global_load_dword v216, v[224:225], off
	v_or_b32_e32 v224, 48, v144
	v_ashrrev_i32_e32 v225, 31, v224
	v_lshl_add_u64 v[224:225], v[224:225], 2, s[8:9]
	global_load_dword v217, v[224:225], off
	global_load_dword v218, v[138:139], off offset:512
	global_load_dword v219, v[138:139], off offset:576
	global_load_dword v220, v[138:139], off offset:640
	global_load_dword v221, v[138:139], off offset:704
	v_readlane_b32 s0, v251, 23
	v_readlane_b32 s1, v251, 24
	v_ashrrev_i32_e32 v147, 31, v146
	s_nop 1
	v_lshl_add_u64 v[222:223], v[146:147], 2, s[0:1]
	global_load_dwordx4 v[188:191], v[222:223], off offset:16
	global_load_dwordx4 v[192:195], v[222:223], off
	v_or_b32_e32 v224, 0x80, v146
	v_ashrrev_i32_e32 v225, 31, v224
	v_lshl_add_u64 v[224:225], v[224:225], 2, s[0:1]
	global_load_dwordx4 v[196:199], v[224:225], off offset:16
	global_load_dwordx4 v[200:203], v[224:225], off
	s_waitcnt vmcnt(0)
	v_fmamk_f32 v140, v214, 0x3a000000, v205
	v_readlane_b32 s0, v251, 23
	v_readlane_b32 s1, v251, 24
	v_ashrrev_i32_e32 v147, 31, v146
	v_rsq_f32_e32 v152, v140
	v_lshl_add_u64 v[140:141], v[146:147], 2, s[0:1]
	v_lshlrev_b64 v[142:143], 14, v[144:145]
	s_waitcnt vmcnt(0)
	v_fma_f32 v145, v121, v152, v189
	v_fma_f32 v124, v124, v152, v192
	v_fma_f32 v125, v125, v152, v193
	v_fma_f32 v126, v126, v152, v194
	v_fma_f32 v187, v127, v152, v195
	v_fma_f32 v127, v120, v152, v188
	v_fma_f32 v157, v123, v152, v191
	v_fma_f32 v153, v122, v152, v190
	v_max_f32_e32 v120, 0, v124
	v_max_f32_e32 v122, 0, v125
	v_max_f32_e32 v121, 0, v126
	v_max_f32_e32 v123, 0, v187
	v_max_f32_e32 v124, 0, v127
	v_max_f32_e32 v126, 0, v145
	v_max_f32_e32 v127, 0, v157
	v_max_f32_e32 v125, 0, v153
	v_pk_mul_f32 v[122:123], v[122:123], v[122:123]
	v_pk_mul_f32 v[126:127], v[126:127], v[126:127]
	v_pk_mul_f32 v[124:125], v[124:125], v[124:125]
	v_pk_mul_f32 v[120:121], v[120:121], v[120:121]
	v_cvt_pk_bf16_f32 v120, v120, v122
	v_cvt_pk_bf16_f32 v121, v121, v123
	v_cvt_pk_bf16_f32 v122, v124, v126
	v_cvt_pk_bf16_f32 v123, v125, v127
	v_lshl_add_u64 v[124:125], s[20:21], 0, v[142:143]
	v_lshlrev_b64 v[142:143], 1, v[146:147]
	v_lshl_add_u64 v[124:125], v[124:125], 0, v[142:143]
	global_store_dwordx4 v[124:125], v[120:123], off
	s_nop 1
	v_or_b32_e32 v120, 0x80, v146
	v_ashrrev_i32_e32 v121, 31, v120
	v_lshl_add_u64 v[126:127], v[120:121], 2, s[0:1]
	v_fma_f32 v123, v115, v152, v199
	v_fma_f32 v116, v116, v152, v200
	v_fma_f32 v117, v117, v152, v201
	v_fma_f32 v118, v118, v152, v202
	v_fma_f32 v157, v119, v152, v203
	v_fma_f32 v119, v112, v152, v196
	v_fma_f32 v120, v113, v152, v197
	v_fma_f32 v121, v114, v152, v198
	v_max_f32_e32 v112, 0, v116
	v_max_f32_e32 v114, 0, v117
	v_max_f32_e32 v113, 0, v118
	v_max_f32_e32 v115, 0, v157
	v_max_f32_e32 v116, 0, v119
	v_max_f32_e32 v118, 0, v120
	v_max_f32_e32 v119, 0, v123
	v_max_f32_e32 v117, 0, v121
	v_pk_mul_f32 v[114:115], v[114:115], v[114:115]
	v_pk_mul_f32 v[118:119], v[118:119], v[118:119]
	v_pk_mul_f32 v[112:113], v[112:113], v[112:113]
	v_pk_mul_f32 v[116:117], v[116:117], v[116:117]
	v_cvt_pk_bf16_f32 v112, v112, v114
	v_cvt_pk_bf16_f32 v113, v113, v115
	v_cvt_pk_bf16_f32 v114, v116, v118
	v_cvt_pk_bf16_f32 v115, v117, v119
	global_store_dwordx4 v[124:125], v[112:115], off offset:256
	s_nop 1
	v_or_b32_e32 v112, 16, v144
	v_ashrrev_i32_e32 v113, 31, v112
	v_lshl_add_u64 v[114:115], v[112:113], 2, s[8:9]
	v_lshlrev_b64 v[112:113], 14, v[112:113]
	v_fmamk_f32 v114, v215, 0x3a000000, v205
	v_rsq_f32_e32 v114, v114
	s_nop 0
	v_fma_f32 v115, v105, v114, v189
	v_fma_f32 v108, v108, v114, v192
	v_fma_f32 v109, v109, v114, v193
	v_fma_f32 v110, v110, v114, v194
	v_fma_f32 v123, v111, v114, v195
	v_fma_f32 v111, v104, v114, v188
	v_fma_f32 v119, v107, v114, v191
	v_fma_f32 v116, v106, v114, v190
	v_max_f32_e32 v104, 0, v108
	v_max_f32_e32 v106, 0, v109
	v_max_f32_e32 v105, 0, v110
	v_max_f32_e32 v107, 0, v123
	v_max_f32_e32 v108, 0, v111
	v_max_f32_e32 v110, 0, v115
	v_max_f32_e32 v111, 0, v119
	v_max_f32_e32 v109, 0, v116
	v_pk_mul_f32 v[106:107], v[106:107], v[106:107]
	v_pk_mul_f32 v[110:111], v[110:111], v[110:111]
	v_pk_mul_f32 v[108:109], v[108:109], v[108:109]
	v_pk_mul_f32 v[104:105], v[104:105], v[104:105]
	v_cvt_pk_bf16_f32 v104, v104, v106
	v_cvt_pk_bf16_f32 v105, v105, v107
	v_cvt_pk_bf16_f32 v106, v108, v110
	v_cvt_pk_bf16_f32 v107, v109, v111
	v_lshl_add_u64 v[108:109], s[20:21], 0, v[112:113]
	v_lshl_add_u64 v[108:109], v[108:109], 0, v[142:143]
	global_store_dwordx4 v[108:109], v[104:107], off
	s_nop 1
	s_nop 0
	v_fma_f32 v107, v99, v114, v199
	v_fma_f32 v100, v100, v114, v200
	v_fma_f32 v101, v101, v114, v201
	v_fma_f32 v102, v102, v114, v202
	v_fma_f32 v113, v103, v114, v203
	v_fma_f32 v103, v96, v114, v196
	v_fma_f32 v104, v97, v114, v197
	v_fma_f32 v105, v98, v114, v198
	v_max_f32_e32 v96, 0, v100
	v_max_f32_e32 v98, 0, v101
	v_max_f32_e32 v97, 0, v102
	v_max_f32_e32 v99, 0, v113
	v_max_f32_e32 v100, 0, v103
	v_max_f32_e32 v102, 0, v104
	v_max_f32_e32 v103, 0, v107
	v_max_f32_e32 v101, 0, v105
	v_pk_mul_f32 v[98:99], v[98:99], v[98:99]
	v_pk_mul_f32 v[102:103], v[102:103], v[102:103]
;     __device__ __forceinline__ void operator()(const f32x4 (&acc)[2][2][4][2], const pg8::Unit& u, int wr, int wc, int fr, int fq) const {
;     ...
;                 const size_t row = (size_t)(row0 + ai * 128 + m * 16);
;                 float ssq = 0.f, rstd = 1.f;
;                 if constexpr (MODE == 8) rstd = 1.f / sqrtf(rs[row] * (1.f / DM) + EPS);
; #pragma unroll
;                 for (int bj = 0; bj < 2; ++bj) {
;                     const int col = col0 + bj * 128;
;                     f32x4 v0 = acc[ai][bj][m][0], v1 = acc[ai][bj][m][1];
;                     if constexpr (MODE == 0 || MODE == 1) { v0 = v0 * scale; v1 = v1 * scale; }
;                     if constexpr (MODE == 6) { float* p = of + row * IDXW + col; *(f32x4*)p = v0; *(f32x4*)(p + 4) = v1; }
;                     else if constexpr (MODE == 0) {
;                         if (u.pn >= COL_BV / 256) {
;                             const float x8[8] = {v0[0], v0[1], v0[2], v0[3], v1[0], v1[1], v1[2], v1[3]};
;                             *(u32x2*)((unsigned char*)aux + row * 1024 + (col - COL_BV)) = to_fp8x8(x8);
;                         } else { u32x4 w; w.x = pk2(v0[0], v0[1]); w.y = pk2(v0[2], v0[3]); w.z = pk2(v1[0], v1[1]); w.w = pk2(v1[2], v1[3]);
;                             *(u32x4*)(ob + row * QKVW + col) = w; }
;                     } else if constexpr (MODE == 1) {
;                         const f32x4 b0 = *(const f32x4*)(vec + col), b1 = *(const f32x4*)(vec + col + 4);
;                         float r[8];
; #pragma unroll
;                         for (int i = 0; i < 4; ++i) { r[i] = 1.f / (1.f + __expf(-(v0[i] + b0[i]))); r[4 + i] = 1.f / (1.f + __expf(-(v1[i] + b1[i]))); }
;                         u32x4 w; w.x = pk2(r[0], r[1]); w.y = pk2(r[2], r[3]); w.z = pk2(r[4], r[5]); w.w = pk2(r[6], r[7]);
;                         *(u32x4*)(ob + row * 4096 + col) = w;
;                     } else if constexpr (MODE == 2 || MODE == 3) {
;                         const u32x4 g = *(const u32x4*)(aux + row * 4096 + (MODE == 3 ? 2048 : 0) + col);
;                         float r[8] = {v0[0], v0[1], v0[2], v0[3], v1[0], v1[1], v1[2], v1[3]};
;                         const unsigned gw[4] = {g.x, g.y, g.z, g.w};
; #pragma unroll
;                         for (int i = 0; i < 4; ++i) { r[2 * i] *= bf2f(gw[i] & 0xffffu); r[2 * i + 1] *= __builtin_bit_cast(float, gw[i] & 0xffff0000u); }
	v_pk_mul_f32 v[96:97], v[96:97], v[96:97]
	v_pk_mul_f32 v[100:101], v[100:101], v[100:101]
	v_cvt_pk_bf16_f32 v96, v96, v98
	v_cvt_pk_bf16_f32 v97, v97, v99
	v_cvt_pk_bf16_f32 v98, v100, v102
	v_cvt_pk_bf16_f32 v99, v101, v103
	global_store_dwordx4 v[108:109], v[96:99], off offset:256
	s_nop 1
	v_or_b32_e32 v96, 32, v144
	v_ashrrev_i32_e32 v97, 31, v96
	v_lshl_add_u64 v[98:99], v[96:97], 2, s[8:9]
	v_lshlrev_b64 v[96:97], 14, v[96:97]
	v_fmamk_f32 v98, v216, 0x3a000000, v205
	v_rsq_f32_e32 v98, v98
	s_nop 0
	v_fma_f32 v99, v89, v98, v189
	v_fma_f32 v92, v92, v98, v192
	v_fma_f32 v93, v93, v98, v193
	v_fma_f32 v94, v94, v98, v194
	v_fma_f32 v107, v95, v98, v195
	v_fma_f32 v95, v88, v98, v188
	v_fma_f32 v103, v91, v98, v191
	v_fma_f32 v100, v90, v98, v190
	v_max_f32_e32 v88, 0, v92
	v_max_f32_e32 v90, 0, v93
	v_max_f32_e32 v89, 0, v94
	v_max_f32_e32 v91, 0, v107
	v_max_f32_e32 v92, 0, v95
	v_max_f32_e32 v94, 0, v99
	v_max_f32_e32 v95, 0, v103
	v_max_f32_e32 v93, 0, v100
	v_pk_mul_f32 v[90:91], v[90:91], v[90:91]
	v_pk_mul_f32 v[94:95], v[94:95], v[94:95]
	v_pk_mul_f32 v[92:93], v[92:93], v[92:93]
	v_pk_mul_f32 v[88:89], v[88:89], v[88:89]
	v_cvt_pk_bf16_f32 v88, v88, v90
	v_cvt_pk_bf16_f32 v89, v89, v91
	v_cvt_pk_bf16_f32 v90, v92, v94
	v_cvt_pk_bf16_f32 v91, v93, v95
	v_lshl_add_u64 v[92:93], s[20:21], 0, v[96:97]
	v_lshl_add_u64 v[92:93], v[92:93], 0, v[142:143]
	global_store_dwordx4 v[92:93], v[88:91], off
	s_nop 1
	s_nop 0
	v_fma_f32 v91, v83, v98, v199
	v_fma_f32 v84, v84, v98, v200
	v_fma_f32 v85, v85, v98, v201
	v_fma_f32 v86, v86, v98, v202
	v_fma_f32 v97, v87, v98, v203
	v_fma_f32 v87, v80, v98, v196
	v_fma_f32 v88, v81, v98, v197
	v_fma_f32 v89, v82, v98, v198
	v_max_f32_e32 v80, 0, v84
	v_max_f32_e32 v82, 0, v85
	v_max_f32_e32 v81, 0, v86
	v_max_f32_e32 v83, 0, v97
	v_max_f32_e32 v84, 0, v87
	v_max_f32_e32 v86, 0, v88
	v_max_f32_e32 v87, 0, v91
	v_max_f32_e32 v85, 0, v89
	v_pk_mul_f32 v[82:83], v[82:83], v[82:83]
	v_pk_mul_f32 v[86:87], v[86:87], v[86:87]
	v_pk_mul_f32 v[80:81], v[80:81], v[80:81]
	v_pk_mul_f32 v[84:85], v[84:85], v[84:85]
	v_cvt_pk_bf16_f32 v80, v80, v82
	v_cvt_pk_bf16_f32 v81, v81, v83
	v_cvt_pk_bf16_f32 v82, v84, v86
	v_cvt_pk_bf16_f32 v83, v85, v87
	global_store_dwordx4 v[92:93], v[80:83], off offset:256
	s_nop 1
	v_or_b32_e32 v80, 48, v144
	v_ashrrev_i32_e32 v81, 31, v80
	v_lshl_add_u64 v[82:83], v[80:81], 2, s[8:9]
	v_lshlrev_b64 v[80:81], 14, v[80:81]
	v_fmamk_f32 v82, v217, 0x3a000000, v205
	v_rsq_f32_e32 v82, v82
	s_nop 0
	v_fma_f32 v83, v73, v82, v189
	v_fma_f32 v76, v76, v82, v192
	v_fma_f32 v77, v77, v82, v193
	v_fma_f32 v78, v78, v82, v194
	v_fma_f32 v91, v79, v82, v195
	v_fma_f32 v79, v72, v82, v188
	v_fma_f32 v87, v75, v82, v191
	v_fma_f32 v84, v74, v82, v190
	v_max_f32_e32 v72, 0, v76
	v_max_f32_e32 v74, 0, v77
	v_max_f32_e32 v73, 0, v78
	v_max_f32_e32 v75, 0, v91
	v_max_f32_e32 v76, 0, v79
	v_max_f32_e32 v78, 0, v83
	v_max_f32_e32 v79, 0, v87
	v_max_f32_e32 v77, 0, v84
	v_pk_mul_f32 v[74:75], v[74:75], v[74:75]
	v_pk_mul_f32 v[78:79], v[78:79], v[78:79]
	v_pk_mul_f32 v[76:77], v[76:77], v[76:77]
	v_pk_mul_f32 v[72:73], v[72:73], v[72:73]
	v_cvt_pk_bf16_f32 v72, v72, v74
	v_cvt_pk_bf16_f32 v73, v73, v75
	v_cvt_pk_bf16_f32 v74, v76, v78
	v_cvt_pk_bf16_f32 v75, v77, v79
	v_lshl_add_u64 v[76:77], s[20:21], 0, v[80:81]
	v_lshl_add_u64 v[76:77], v[76:77], 0, v[142:143]
	global_store_dwordx4 v[76:77], v[72:75], off
	s_nop 1
	s_nop 0
	v_fma_f32 v75, v67, v82, v199
	v_fma_f32 v68, v68, v82, v200
	v_fma_f32 v69, v69, v82, v201
	v_fma_f32 v70, v70, v82, v202
	v_fma_f32 v81, v71, v82, v203
	v_fma_f32 v71, v64, v82, v196
	v_fma_f32 v72, v65, v82, v197
	v_fma_f32 v73, v66, v82, v198
	v_max_f32_e32 v64, 0, v68
	v_max_f32_e32 v66, 0, v69
	v_max_f32_e32 v65, 0, v70
	v_max_f32_e32 v67, 0, v81
	v_max_f32_e32 v68, 0, v71
	v_max_f32_e32 v70, 0, v72
	v_max_f32_e32 v71, 0, v75
	v_max_f32_e32 v69, 0, v73
	v_pk_mul_f32 v[66:67], v[66:67], v[66:67]
	v_pk_mul_f32 v[70:71], v[70:71], v[70:71]
	v_pk_mul_f32 v[64:65], v[64:65], v[64:65]
	v_pk_mul_f32 v[68:69], v[68:69], v[68:69]
	v_cvt_pk_bf16_f32 v64, v64, v66
	v_cvt_pk_bf16_f32 v65, v65, v67
	v_cvt_pk_bf16_f32 v66, v68, v70
	v_cvt_pk_bf16_f32 v67, v69, v71
	global_store_dwordx4 v[76:77], v[64:67], off offset:256
	s_nop 1
	v_fmamk_f32 v64, v218, 0x3a000000, v205
	s_mov_b64 s[0:1], 0x200000
	v_rsq_f32_e32 v64, v64
	s_nop 0
	v_fma_f32 v65, v57, v64, v189
	v_fma_f32 v60, v60, v64, v192
	v_fma_f32 v61, v61, v64, v193
	v_fma_f32 v62, v62, v64, v194
	v_fma_f32 v73, v63, v64, v195
	v_fma_f32 v63, v56, v64, v188
	v_fma_f32 v69, v59, v64, v191
	v_fma_f32 v66, v58, v64, v190
	v_max_f32_e32 v56, 0, v60
	v_max_f32_e32 v58, 0, v61
	v_max_f32_e32 v57, 0, v62
	v_max_f32_e32 v59, 0, v73
	v_max_f32_e32 v60, 0, v63
	v_max_f32_e32 v62, 0, v65
	v_max_f32_e32 v63, 0, v69
	v_max_f32_e32 v61, 0, v66
	v_pk_mul_f32 v[58:59], v[58:59], v[58:59]
	v_pk_mul_f32 v[62:63], v[62:63], v[62:63]
	v_pk_mul_f32 v[60:61], v[60:61], v[60:61]
	v_bfe_u32 v67, v59, 16, 1
	v_bfe_u32 v68, v58, 16, 1
	v_add3_u32 v68, v58, v68, s33
	v_add3_u32 v67, v59, v67, s33
	v_pk_mul_f32 v[56:57], v[56:57], v[56:57]
	v_cvt_pk_bf16_f32 v59, v61, v63
	v_cvt_pk_bf16_f32 v58, v60, v62
	v_bfe_u32 v62, v56, 16, 1
	v_bfe_u32 v63, v57, 16, 1
	v_add3_u32 v57, v57, v63, s33
	v_add3_u32 v56, v56, v62, s33
	v_lshl_add_u64 v[60:61], v[124:125], 0, s[0:1]
	s_mov_b32 s0, 0x200000
	v_lshrrev_b32_e32 v56, 16, v56
	v_lshrrev_b32_e32 v57, 16, v57
	v_add_co_u32_e32 v62, vcc, s0, v124
	v_and_or_b32 v57, v67, s67, v57
	v_and_or_b32 v56, v68, s67, v56
	v_addc_co_u32_e32 v63, vcc, 0, v125, vcc
	global_store_dwordx4 v[62:63], v[56:59], off
	s_nop 1
;     __device__ __forceinline__ void operator()(const f32x4 (&acc)[2][2][4][2], const pg8::Unit& u, int wr, int wc, int fr, int fq) const {
;     ...
;                 const size_t row = (size_t)(row0 + ai * 128 + m * 16);
;                 float ssq = 0.f, rstd = 1.f;
;                 if constexpr (MODE == 8) rstd = 1.f / sqrtf(rs[row] * (1.f / DM) + EPS);
; #pragma unroll
;                 for (int bj = 0; bj < 2; ++bj) {
;                     const int col = col0 + bj * 128;
;                     f32x4 v0 = acc[ai][bj][m][0], v1 = acc[ai][bj][m][1];
;                     if constexpr (MODE == 0 || MODE == 1) { v0 = v0 * scale; v1 = v1 * scale; }
;                     if constexpr (MODE == 6) { float* p = of + row * IDXW + col; *(f32x4*)p = v0; *(f32x4*)(p + 4) = v1; }
;                     else if constexpr (MODE == 0) {
;                         if (u.pn >= COL_BV / 256) {
;                             const float x8[8] = {v0[0], v0[1], v0[2], v0[3], v1[0], v1[1], v1[2], v1[3]};
;                             *(u32x2*)((unsigned char*)aux + row * 1024 + (col - COL_BV)) = to_fp8x8(x8);
;                         } else { u32x4 w; w.x = pk2(v0[0], v0[1]); w.y = pk2(v0[2], v0[3]); w.z = pk2(v1[0], v1[1]); w.w = pk2(v1[2], v1[3]);
;                             *(u32x4*)(ob + row * QKVW + col) = w; }
;                     } else if constexpr (MODE == 1) {
;                         const f32x4 b0 = *(const f32x4*)(vec + col), b1 = *(const f32x4*)(vec + col + 4);
;                         float r[8];
; #pragma unroll
;                         for (int i = 0; i < 4; ++i) { r[i] = 1.f / (1.f + __expf(-(v0[i] + b0[i]))); r[4 + i] = 1.f / (1.f + __expf(-(v1[i] + b1[i]))); }
;                         u32x4 w; w.x = pk2(r[0], r[1]); w.y = pk2(r[2], r[3]); w.z = pk2(r[4], r[5]); w.w = pk2(r[6], r[7]);
;                         *(u32x4*)(ob + row * 4096 + col) = w;
;                     } else if constexpr (MODE == 2 || MODE == 3) {
;                         const u32x4 g = *(const u32x4*)(aux + row * 4096 + (MODE == 3 ? 2048 : 0) + col);
;                         float r[8] = {v0[0], v0[1], v0[2], v0[3], v1[0], v1[1], v1[2], v1[3]};
;                         const unsigned gw[4] = {g.x, g.y, g.z, g.w};
; #pragma unroll
;                         for (int i = 0; i < 4; ++i) { r[2 * i] *= bf2f(gw[i] & 0xffffu); r[2 * i + 1] *= __builtin_bit_cast(float, gw[i] & 0xffff0000u); }
	s_nop 0
	v_fma_f32 v59, v51, v64, v199
	v_fma_f32 v52, v52, v64, v200
	v_fma_f32 v53, v53, v64, v201
	v_fma_f32 v54, v54, v64, v202
	v_fma_f32 v69, v55, v64, v203
	v_fma_f32 v55, v48, v64, v196
	v_fma_f32 v56, v49, v64, v197
	v_fma_f32 v57, v50, v64, v198
	v_max_f32_e32 v48, 0, v52
	v_max_f32_e32 v50, 0, v53
	v_max_f32_e32 v49, 0, v54
	v_max_f32_e32 v51, 0, v69
	v_max_f32_e32 v52, 0, v55
	v_max_f32_e32 v54, 0, v56
	v_max_f32_e32 v55, 0, v59
	v_max_f32_e32 v53, 0, v57
	v_pk_mul_f32 v[50:51], v[50:51], v[50:51]
	v_pk_mul_f32 v[54:55], v[54:55], v[54:55]
	v_pk_mul_f32 v[48:49], v[48:49], v[48:49]
	v_pk_mul_f32 v[52:53], v[52:53], v[52:53]
	v_cvt_pk_bf16_f32 v48, v48, v50
	v_cvt_pk_bf16_f32 v49, v49, v51
	v_cvt_pk_bf16_f32 v50, v52, v54
	v_cvt_pk_bf16_f32 v51, v53, v55
	global_store_dwordx4 v[60:61], v[48:51], off offset:256
	s_nop 1
	v_fmamk_f32 v48, v219, 0x3a000000, v205
	s_mov_b64 s[0:1], 0x240000
	v_rsq_f32_e32 v48, v48
	s_nop 0
	v_fma_f32 v49, v41, v48, v189
	v_fma_f32 v44, v44, v48, v192
	v_fma_f32 v45, v45, v48, v193
	v_fma_f32 v46, v46, v48, v194
	v_fma_f32 v57, v47, v48, v195
	v_fma_f32 v47, v40, v48, v188
	v_fma_f32 v53, v43, v48, v191
	v_fma_f32 v50, v42, v48, v190
	v_max_f32_e32 v40, 0, v44
	v_max_f32_e32 v42, 0, v45
	v_max_f32_e32 v41, 0, v46
	v_max_f32_e32 v43, 0, v57
	v_max_f32_e32 v44, 0, v47
	v_max_f32_e32 v46, 0, v49
	v_max_f32_e32 v47, 0, v53
	v_max_f32_e32 v45, 0, v50
	v_pk_mul_f32 v[42:43], v[42:43], v[42:43]
	v_pk_mul_f32 v[46:47], v[46:47], v[46:47]
	v_pk_mul_f32 v[44:45], v[44:45], v[44:45]
	v_bfe_u32 v51, v43, 16, 1
	v_bfe_u32 v52, v42, 16, 1
	v_add3_u32 v52, v42, v52, s33
	v_add3_u32 v51, v43, v51, s33
	v_pk_mul_f32 v[40:41], v[40:41], v[40:41]
	v_cvt_pk_bf16_f32 v43, v45, v47
	v_cvt_pk_bf16_f32 v42, v44, v46
	v_bfe_u32 v46, v40, 16, 1
	v_bfe_u32 v47, v41, 16, 1
	v_add3_u32 v41, v41, v47, s33
	v_add3_u32 v40, v40, v46, s33
	v_lshl_add_u64 v[44:45], v[124:125], 0, s[0:1]
	s_mov_b32 s0, 0x240000
	v_lshrrev_b32_e32 v40, 16, v40
	v_lshrrev_b32_e32 v41, 16, v41
	v_add_co_u32_e32 v46, vcc, s0, v124
	v_and_or_b32 v41, v51, s67, v41
	v_and_or_b32 v40, v52, s67, v40
	v_addc_co_u32_e32 v47, vcc, 0, v125, vcc
	global_store_dwordx4 v[46:47], v[40:43], off
	s_nop 1
	s_nop 0
	v_fma_f32 v43, v35, v48, v199
	v_fma_f32 v36, v36, v48, v200
	v_fma_f32 v37, v37, v48, v201
	v_fma_f32 v38, v38, v48, v202
	v_fma_f32 v53, v39, v48, v203
	v_fma_f32 v39, v32, v48, v196
	v_fma_f32 v40, v33, v48, v197
	v_fma_f32 v41, v34, v48, v198
	v_max_f32_e32 v32, 0, v36
	v_max_f32_e32 v34, 0, v37
	v_max_f32_e32 v33, 0, v38
	v_max_f32_e32 v35, 0, v53
	v_max_f32_e32 v36, 0, v39
	v_max_f32_e32 v38, 0, v40
	v_max_f32_e32 v39, 0, v43
	v_max_f32_e32 v37, 0, v41
	v_pk_mul_f32 v[34:35], v[34:35], v[34:35]
	v_pk_mul_f32 v[38:39], v[38:39], v[38:39]
	v_pk_mul_f32 v[32:33], v[32:33], v[32:33]
	v_pk_mul_f32 v[36:37], v[36:37], v[36:37]
	v_cvt_pk_bf16_f32 v32, v32, v34
	v_cvt_pk_bf16_f32 v33, v33, v35
	v_cvt_pk_bf16_f32 v34, v36, v38
	v_cvt_pk_bf16_f32 v35, v37, v39
	global_store_dwordx4 v[44:45], v[32:35], off offset:256
	s_nop 1
	v_fmamk_f32 v32, v220, 0x3a000000, v205
	s_mov_b64 s[0:1], 0x280000
	v_rsq_f32_e32 v32, v32
	s_nop 0
	v_fma_f32 v33, v25, v32, v189
	v_fma_f32 v28, v28, v32, v192
	v_fma_f32 v29, v29, v32, v193
	v_fma_f32 v30, v30, v32, v194
	v_fma_f32 v41, v31, v32, v195
	v_fma_f32 v31, v24, v32, v188
	v_fma_f32 v37, v27, v32, v191
	v_fma_f32 v34, v26, v32, v190
	v_max_f32_e32 v24, 0, v28
	v_max_f32_e32 v26, 0, v29
	v_max_f32_e32 v25, 0, v30
	v_max_f32_e32 v27, 0, v41
	v_max_f32_e32 v28, 0, v31
	v_max_f32_e32 v30, 0, v33
	v_max_f32_e32 v31, 0, v37
	v_max_f32_e32 v29, 0, v34
	v_pk_mul_f32 v[26:27], v[26:27], v[26:27]
	v_pk_mul_f32 v[30:31], v[30:31], v[30:31]
	v_pk_mul_f32 v[28:29], v[28:29], v[28:29]
	v_bfe_u32 v35, v27, 16, 1
; #define PG8_BAR __builtin_amdgcn_s_barrier()
; __device__ __forceinline__ unsigned pk2(float lo, float hi) { return f2bf(lo) | (f2bf(hi) << 16); }
; template <class Epi, class Sched, bool ALIGN_EPI = false, bool SP2 = false, bool F8 = false>
; __device__ __forceinline__ void gemm_phase(PG8_LAS unsigned char* lds, const Gemm g, const Sched& S, const Epi& E) {
;     ...
;         cur = nxt; cA = nA; cB = nB; ++ui;
;         if constexpr (ALIGN_EPI) { if (wr == 1) PG8_BAR; }
;     __device__ __forceinline__ void operator()(const f32x4 (&acc)[2][2][4][2], const pg8::Unit& u, int wr, int wc, int fr, int fq) const {
;     ...
;                     } else if constexpr (MODE == 8) {
;                         const f32x4 b0 = *(const f32x4*)(vec + col), b1 = *(const f32x4*)(vec + col + 4);
;                         float r[8] = {v0[0] * rstd + b0[0], v0[1] * rstd + b0[1], v0[2] * rstd + b0[2], v0[3] * rstd + b0[3], v1[0] * rstd + b1[0], v1[1] * rstd + b1[1], v1[2] * rstd + b1[2], v1[3] * rstd + b1[3]};
; #pragma unroll
;                         for (int i = 0; i < 8; ++i) { const float q = fmaxf(r[i], 0.f); r[i] = q * q; }
;                         u32x4 w; w.x = pk2(r[0], r[1]); w.y = pk2(r[2], r[3]); w.z = pk2(r[4], r[5]); w.w = pk2(r[6], r[7]);
;                         *(u32x4*)(ob + row * HIDN + col) = w;
	v_bfe_u32 v36, v26, 16, 1
	v_add3_u32 v36, v26, v36, s33
	v_add3_u32 v35, v27, v35, s33
	v_pk_mul_f32 v[24:25], v[24:25], v[24:25]
	v_cvt_pk_bf16_f32 v27, v29, v31
	v_cvt_pk_bf16_f32 v26, v28, v30
	v_bfe_u32 v30, v24, 16, 1
	v_bfe_u32 v31, v25, 16, 1
	v_add3_u32 v25, v25, v31, s33
	v_add3_u32 v24, v24, v30, s33
	v_lshl_add_u64 v[28:29], v[124:125], 0, s[0:1]
	s_mov_b32 s0, 0x280000
	v_lshrrev_b32_e32 v24, 16, v24
	v_lshrrev_b32_e32 v25, 16, v25
	v_add_co_u32_e32 v30, vcc, s0, v124
	v_and_or_b32 v25, v35, s67, v25
	v_and_or_b32 v24, v36, s67, v24
	v_addc_co_u32_e32 v31, vcc, 0, v125, vcc
	global_store_dwordx4 v[30:31], v[24:27], off
	s_nop 1
	s_nop 0
	v_fma_f32 v27, v19, v32, v199
	v_fma_f32 v20, v20, v32, v200
	v_fma_f32 v21, v21, v32, v201
	v_fma_f32 v22, v22, v32, v202
	v_fma_f32 v37, v23, v32, v203
	v_fma_f32 v23, v16, v32, v196
	v_fma_f32 v24, v17, v32, v197
	v_fma_f32 v25, v18, v32, v198
	v_max_f32_e32 v16, 0, v20
	v_max_f32_e32 v18, 0, v21
	v_max_f32_e32 v17, 0, v22
	v_max_f32_e32 v19, 0, v37
	v_max_f32_e32 v20, 0, v23
	v_max_f32_e32 v22, 0, v24
	v_max_f32_e32 v23, 0, v27
	v_max_f32_e32 v21, 0, v25
	v_pk_mul_f32 v[18:19], v[18:19], v[18:19]
	v_pk_mul_f32 v[22:23], v[22:23], v[22:23]
	v_pk_mul_f32 v[16:17], v[16:17], v[16:17]
	v_pk_mul_f32 v[20:21], v[20:21], v[20:21]
	v_cvt_pk_bf16_f32 v16, v16, v18
	v_cvt_pk_bf16_f32 v17, v17, v19
	v_cvt_pk_bf16_f32 v18, v20, v22
	v_cvt_pk_bf16_f32 v19, v21, v23
	global_store_dwordx4 v[28:29], v[16:19], off offset:256
	s_nop 1
	v_fmamk_f32 v16, v221, 0x3a000000, v205
	s_mov_b64 s[0:1], 0x2c0000
	v_rsq_f32_e32 v16, v16
	s_nop 0
	v_fma_f32 v17, v9, v16, v189
	v_fma_f32 v12, v12, v16, v192
	v_fma_f32 v13, v13, v16, v193
	v_fma_f32 v14, v14, v16, v194
	v_fma_f32 v25, v15, v16, v195
	v_fma_f32 v15, v8, v16, v188
	v_fma_f32 v21, v11, v16, v191
	v_fma_f32 v18, v10, v16, v190
	v_max_f32_e32 v8, 0, v12
	v_max_f32_e32 v10, 0, v13
	v_max_f32_e32 v9, 0, v14
	v_max_f32_e32 v11, 0, v25
	v_max_f32_e32 v12, 0, v15
	v_max_f32_e32 v14, 0, v17
	v_max_f32_e32 v15, 0, v21
	v_max_f32_e32 v13, 0, v18
	v_pk_mul_f32 v[10:11], v[10:11], v[10:11]
	v_pk_mul_f32 v[14:15], v[14:15], v[14:15]
	v_pk_mul_f32 v[12:13], v[12:13], v[12:13]
	v_bfe_u32 v19, v11, 16, 1
	v_bfe_u32 v20, v10, 16, 1
	v_add3_u32 v20, v10, v20, s33
	v_add3_u32 v19, v11, v19, s33
	v_pk_mul_f32 v[8:9], v[8:9], v[8:9]
	v_cvt_pk_bf16_f32 v11, v13, v15
	v_cvt_pk_bf16_f32 v10, v12, v14
	v_bfe_u32 v14, v8, 16, 1
	v_bfe_u32 v15, v9, 16, 1
	v_add3_u32 v9, v9, v15, s33
	v_add3_u32 v8, v8, v14, s33
	v_lshl_add_u64 v[12:13], v[124:125], 0, s[0:1]
	s_mov_b32 s0, 0x2c0000
	v_lshrrev_b32_e32 v8, 16, v8
	v_lshrrev_b32_e32 v9, 16, v9
	v_add_co_u32_e32 v14, vcc, s0, v124
	v_and_or_b32 v9, v19, s67, v9
	v_and_or_b32 v8, v20, s67, v8
	v_addc_co_u32_e32 v15, vcc, 0, v125, vcc
	global_store_dwordx4 v[14:15], v[8:11], off
	s_nop 0
	s_mov_b64 s[0:1], -1
	s_andn2_b64 vcc, exec, s[38:39]
	v_fma_f32 v11, v3, v16, v199
	v_fma_f32 v4, v4, v16, v200
	v_fma_f32 v5, v5, v16, v201
	v_fma_f32 v6, v6, v16, v202
	v_fma_f32 v21, v7, v16, v203
	v_fma_f32 v7, v0, v16, v196
	v_fma_f32 v8, v1, v16, v197
	v_fma_f32 v9, v2, v16, v198
	v_max_f32_e32 v0, 0, v4
	v_max_f32_e32 v2, 0, v5
	v_max_f32_e32 v1, 0, v6
	v_max_f32_e32 v3, 0, v21
	v_max_f32_e32 v4, 0, v7
	v_max_f32_e32 v6, 0, v8
	v_max_f32_e32 v7, 0, v11
	v_max_f32_e32 v5, 0, v9
	v_pk_mul_f32 v[2:3], v[2:3], v[2:3]
	v_pk_mul_f32 v[6:7], v[6:7], v[6:7]
	v_pk_mul_f32 v[0:1], v[0:1], v[0:1]
	v_pk_mul_f32 v[4:5], v[4:5], v[4:5]
	v_cvt_pk_bf16_f32 v0, v0, v2
	v_cvt_pk_bf16_f32 v1, v1, v3
	v_cvt_pk_bf16_f32 v2, v4, v6
	v_cvt_pk_bf16_f32 v3, v5, v7
	global_store_dwordx4 v[12:13], v[0:3], off offset:256
	s_cbranch_vccnz .LBB0_24
	s_andn2_b64 vcc, exec, s[42:43]
	s_cbranch_vccnz .LBB0_23
	s_barrier
	s_branch .LBB0_23
